# adds E8: EpiRes residual loads no longer drain the LDS-DMA prefetch first (stacked on E1,E4,E5,E6,E7)
# baseline (speedup 1.0000x reference)
.LBB0_412:
	v_ashrrev_i32_e32 v227, 31, v226
	v_ashrrev_i32_e32 v225, 31, v224
	v_lshlrev_b64 v[136:137], 11, v[226:227]
	v_lshlrev_b64 v[144:145], 11, v[224:225]
	v_lshl_add_u64 v[132:133], v[228:229], 1, v[218:219]
	v_lshl_add_u64 v[140:141], v[218:219], 0, v[136:137]
	v_lshl_add_u64 v[148:149], v[218:219], 0, v[144:145]
	v_ashrrev_i32_e32 v223, 31, v222
	global_load_dwordx4 v[128:131], v[132:133], off
	s_nop 0
	global_load_dwordx4 v[132:135], v[132:133], off offset:256
	s_nop 0
	global_load_dwordx4 v[136:139], v[140:141], off
	s_nop 0
	global_load_dwordx4 v[140:143], v[140:141], off offset:256
	s_nop 0
	global_load_dwordx4 v[144:147], v[148:149], off
	global_load_dwordx4 v[244:247], v[148:149], off offset:256
	v_lshlrev_b64 v[148:149], 11, v[222:223]
	v_lshl_add_u64 v[148:149], v[218:219], 0, v[148:149]
	global_load_dwordx4 v[194:197], v[148:149], off
	global_load_dwordx4 v[198:201], v[148:149], off offset:256
	s_waitcnt vmcnt(7)
	v_lshlrev_b32_e32 v188, 16, v128
	v_and_b32_e32 v189, 0xffff0000, v128
	v_lshlrev_b32_e32 v190, 16, v129
	v_and_b32_e32 v191, 0xffff0000, v129
	v_lshlrev_b32_e32 v184, 16, v130
	v_and_b32_e32 v185, 0xffff0000, v130
	v_lshlrev_b32_e32 v186, 16, v131
	v_and_b32_e32 v187, 0xffff0000, v131
	s_waitcnt vmcnt(6)
	v_lshlrev_b32_e32 v180, 16, v132
	v_and_b32_e32 v181, 0xffff0000, v132
	v_lshlrev_b32_e32 v182, 16, v133
	v_and_b32_e32 v183, 0xffff0000, v133
	v_lshlrev_b32_e32 v176, 16, v134
	v_and_b32_e32 v177, 0xffff0000, v134
	v_lshlrev_b32_e32 v178, 16, v135
	v_and_b32_e32 v179, 0xffff0000, v135
	s_waitcnt vmcnt(5)
	v_lshlrev_b32_e32 v172, 16, v136
	v_and_b32_e32 v173, 0xffff0000, v136
	v_lshlrev_b32_e32 v174, 16, v137
	v_and_b32_e32 v175, 0xffff0000, v137
	v_lshlrev_b32_e32 v168, 16, v138
	v_and_b32_e32 v169, 0xffff0000, v138
	v_lshlrev_b32_e32 v170, 16, v139
	v_and_b32_e32 v171, 0xffff0000, v139
	s_waitcnt vmcnt(4)
	v_lshlrev_b32_e32 v164, 16, v140
	v_and_b32_e32 v165, 0xffff0000, v140
	v_lshlrev_b32_e32 v166, 16, v141
	v_and_b32_e32 v167, 0xffff0000, v141
	v_lshlrev_b32_e32 v160, 16, v142
	v_and_b32_e32 v161, 0xffff0000, v142
	v_lshlrev_b32_e32 v162, 16, v143
	v_and_b32_e32 v163, 0xffff0000, v143
	s_waitcnt vmcnt(3)
	v_lshlrev_b32_e32 v156, 16, v144
	v_and_b32_e32 v157, 0xffff0000, v144
	v_lshlrev_b32_e32 v158, 16, v145
	v_and_b32_e32 v159, 0xffff0000, v145
	v_lshlrev_b32_e32 v152, 16, v146
	v_and_b32_e32 v153, 0xffff0000, v146
	v_lshlrev_b32_e32 v154, 16, v147
	v_and_b32_e32 v155, 0xffff0000, v147
	s_waitcnt vmcnt(2)
	v_lshlrev_b32_e32 v148, 16, v244
	v_and_b32_e32 v149, 0xffff0000, v244
	v_lshlrev_b32_e32 v150, 16, v245
	v_and_b32_e32 v151, 0xffff0000, v245
	v_lshlrev_b32_e32 v144, 16, v246
	v_and_b32_e32 v145, 0xffff0000, v246
	v_lshlrev_b32_e32 v146, 16, v247
	v_and_b32_e32 v147, 0xffff0000, v247
	s_waitcnt vmcnt(1)
	v_lshlrev_b32_e32 v140, 16, v194
	v_and_b32_e32 v141, 0xffff0000, v194
	v_lshlrev_b32_e32 v142, 16, v195
	v_and_b32_e32 v143, 0xffff0000, v195
	v_lshlrev_b32_e32 v136, 16, v196
	v_and_b32_e32 v137, 0xffff0000, v196
	v_lshlrev_b32_e32 v138, 16, v197
	v_and_b32_e32 v139, 0xffff0000, v197
	s_waitcnt vmcnt(0)
	v_lshlrev_b32_e32 v132, 16, v198
	v_and_b32_e32 v133, 0xffff0000, v198
	v_lshlrev_b32_e32 v134, 16, v199
	v_and_b32_e32 v135, 0xffff0000, v199
	v_lshlrev_b32_e32 v128, 16, v200
	v_and_b32_e32 v129, 0xffff0000, v200
	v_lshlrev_b32_e32 v130, 16, v201
	v_and_b32_e32 v131, 0xffff0000, v201
